# speedup vs baseline: 1.0059x; 1.0059x over previous
.LBB0_252:
	s_or_b64 exec, exec, s[46:47]
	v_and_b32_e32 v131, 15, v204
	v_lshlrev_b32_e32 v4, 2, v204
	v_and_b32_e32 v2, 48, v204
	v_lshlrev_b32_e32 v3, 6, v131
	v_and_b32_e32 v4, 32, v4
	v_bitop3_b32 v238, v2, v4, v3 bitop3:0x36
	v_lshlrev_b32_e32 v2, 13, v130
	v_add3_u32 v237, 0, v2, v238
	v_lshlrev_b32_e32 v2, 6, v204
	v_and_b32_e32 v2, 0x3000, v2
	s_add_i32 s2, 0, 0x10000
	v_add_u32_e32 v239, s2, v2
	s_lshr_b32 s2, s31, 26
	s_add_i32 s2, s30, s2
	v_add_u32_e32 v242, 0x18000, v232
	s_ashr_i32 s33, s2, 6
	v_readfirstlane_b32 s2, v242
	v_add_u32_e32 v243, 0x1a000, v232
	s_mov_b32 s46, s26
	s_mov_b32 s47, s27
	s_mov_b32 m0, s2
	v_readfirstlane_b32 s31, v243
	v_add_u32_e32 v244, 0x8000, v232
	s_waitcnt vmcnt(0)
	s_barrier
	buffer_load_dwordx4 v0, s[44:47], s17 offen lds
	s_add_i32 s2, s8, 0x80
	s_mov_b32 m0, s31
	v_readfirstlane_b32 s31, v244
	v_add_u32_e32 v245, 0xa000, v232
	buffer_load_dwordx4 v0, s[44:47], s2 offen lds
	s_mov_b32 m0, s31
	v_readfirstlane_b32 s31, v245
	v_add_u32_e32 v246, 0x1c000, v232
	buffer_load_dwordx4 v0, s[24:27], s17 offen lds
	s_mov_b32 m0, s31
	s_lshl_b32 s58, s30, 8
	v_readfirstlane_b32 s31, v246
	v_add_u32_e32 v247, 0x1e000, v232
	buffer_load_dwordx4 v0, s[24:27], s2 offen lds
	s_or_b32 s2, s58, 0x80
	s_mov_b32 m0, s31
	v_readfirstlane_b32 s31, v247
	buffer_load_dwordx4 v0, s[44:47], s2 offen lds
	s_add_i32 s2, s2, s8
	s_mov_b32 m0, s31
	v_mov_b32_e32 v5, 0
	buffer_load_dwordx4 v0, s[44:47], s2 offen lds
	s_waitcnt vmcnt(6)
	s_cmpk_lt_i32 s30, 0xc0
	v_add_u32_e32 v241, 0xc000, v232
	v_add_u32_e32 v240, 0xe000, v232
	v_mov_b32_e32 v4, v5
	v_mov_b32_e32 v3, v5
	v_mov_b32_e32 v2, v5
	v_mov_b32_e32 v9, v5
	v_mov_b32_e32 v8, v5
	v_mov_b32_e32 v7, v5
	v_mov_b32_e32 v6, v5
	v_mov_b32_e32 v13, v5
	v_mov_b32_e32 v12, v5
	v_mov_b32_e32 v11, v5
	v_mov_b32_e32 v10, v5
	v_mov_b32_e32 v17, v5
	v_mov_b32_e32 v16, v5
	v_mov_b32_e32 v15, v5
	v_mov_b32_e32 v14, v5
	s_waitcnt vmcnt(13)
	v_mov_b32_e32 v21, v5
	v_mov_b32_e32 v20, v5
	v_mov_b32_e32 v19, v5
	v_mov_b32_e32 v18, v5
	s_waitcnt vmcnt(12)
	v_mov_b32_e32 v25, v5
	v_mov_b32_e32 v24, v5
	v_mov_b32_e32 v23, v5
	v_mov_b32_e32 v22, v5
	s_waitcnt vmcnt(11)
	v_mov_b32_e32 v29, v5
	v_mov_b32_e32 v28, v5
	v_mov_b32_e32 v27, v5
	v_mov_b32_e32 v26, v5
	s_waitcnt vmcnt(10)
	v_mov_b32_e32 v33, v5
	v_mov_b32_e32 v32, v5
	v_mov_b32_e32 v31, v5
	v_mov_b32_e32 v30, v5
	v_mov_b32_e32 v37, v5
	v_mov_b32_e32 v36, v5
	v_mov_b32_e32 v35, v5
	v_mov_b32_e32 v34, v5
	v_mov_b32_e32 v41, v5
	v_mov_b32_e32 v40, v5
	v_mov_b32_e32 v39, v5
	v_mov_b32_e32 v38, v5
	v_mov_b32_e32 v45, v5
	v_mov_b32_e32 v44, v5
	v_mov_b32_e32 v43, v5
	v_mov_b32_e32 v42, v5
	v_mov_b32_e32 v49, v5
	v_mov_b32_e32 v48, v5
	v_mov_b32_e32 v47, v5
	v_mov_b32_e32 v46, v5
	v_mov_b32_e32 v53, v5
	v_mov_b32_e32 v52, v5
	v_mov_b32_e32 v51, v5
	v_mov_b32_e32 v50, v5
	v_mov_b32_e32 v57, v5
	v_mov_b32_e32 v56, v5
	v_mov_b32_e32 v55, v5
	v_mov_b32_e32 v54, v5
	v_mov_b32_e32 v61, v5
	v_mov_b32_e32 v60, v5
	v_mov_b32_e32 v59, v5
	v_mov_b32_e32 v58, v5
	v_mov_b32_e32 v65, v5
	v_mov_b32_e32 v64, v5
	v_mov_b32_e32 v63, v5
	v_mov_b32_e32 v62, v5
	v_mov_b32_e32 v129, v5
	v_mov_b32_e32 v128, v5
	v_mov_b32_e32 v127, v5
	v_mov_b32_e32 v126, v5
	v_mov_b32_e32 v125, v5
	v_mov_b32_e32 v124, v5
	v_mov_b32_e32 v123, v5
	v_mov_b32_e32 v122, v5
	v_mov_b32_e32 v121, v5
	v_mov_b32_e32 v120, v5
	v_mov_b32_e32 v119, v5
	v_mov_b32_e32 v118, v5
	v_mov_b32_e32 v117, v5
	v_mov_b32_e32 v116, v5
	v_mov_b32_e32 v115, v5
	v_mov_b32_e32 v114, v5
	v_mov_b32_e32 v113, v5
	v_mov_b32_e32 v112, v5
	v_mov_b32_e32 v111, v5
	v_mov_b32_e32 v110, v5
	v_mov_b32_e32 v109, v5
	v_mov_b32_e32 v108, v5
	v_mov_b32_e32 v107, v5
	v_mov_b32_e32 v106, v5
	v_mov_b32_e32 v105, v5
	v_mov_b32_e32 v104, v5
	v_mov_b32_e32 v103, v5
	v_mov_b32_e32 v102, v5
	v_mov_b32_e32 v101, v5
	v_mov_b32_e32 v100, v5
	v_mov_b32_e32 v99, v5
	v_mov_b32_e32 v98, v5
	v_mov_b32_e32 v97, v5
	v_mov_b32_e32 v96, v5
	v_mov_b32_e32 v95, v5
	v_mov_b32_e32 v94, v5
	v_mov_b32_e32 v93, v5
	v_mov_b32_e32 v92, v5
	v_mov_b32_e32 v91, v5
	v_mov_b32_e32 v90, v5
	v_mov_b32_e32 v89, v5
	v_mov_b32_e32 v88, v5
	v_mov_b32_e32 v87, v5
	v_mov_b32_e32 v86, v5
	v_mov_b32_e32 v85, v5
	v_mov_b32_e32 v84, v5
	v_mov_b32_e32 v83, v5
	v_mov_b32_e32 v82, v5
	v_mov_b32_e32 v81, v5
	v_mov_b32_e32 v80, v5
	v_mov_b32_e32 v79, v5
	v_mov_b32_e32 v78, v5
	v_mov_b32_e32 v77, v5
	v_mov_b32_e32 v76, v5
	v_mov_b32_e32 v75, v5
	v_mov_b32_e32 v74, v5
	v_mov_b32_e32 v73, v5
	v_mov_b32_e32 v72, v5
	v_mov_b32_e32 v71, v5
	v_mov_b32_e32 v70, v5
	v_mov_b32_e32 v69, v5
	v_mov_b32_e32 v68, v5
	v_mov_b32_e32 v67, v5
	v_mov_b32_e32 v66, v5
	s_barrier
	s_cbranch_scc1 .LBB0_262
	v_lshlrev_b32_e32 v2, 6, v130
	s_add_i32 s59, s33, -2
	v_add3_u32 v2, v131, s60, v2
	s_cmp_eq_u32 s97, 1
	v_mad_i64_i32 v[2:3], s[46:47], v2, s62, 0
	s_cselect_b64 s[30:31], -1, 0
	v_lshrrev_b32_e32 v5, 1, v204
	s_lshl_b64 s[46:47], s[94:95], 1
	v_and_b32_e32 v4, 0xc0, v204
	v_and_b32_e32 v5, 24, v5
	s_add_u32 s46, s15, s46
	v_or3_b32 v2, v2, v4, v5
	s_addc_u32 s47, s16, s47
	v_mov_b32_e32 v66, 0
	v_lshl_add_u64 v[130:131], s[46:47], 0, v[2:3]
	s_mov_b32 s2, 0
	s_movk_i32 s70, 0x100
	v_mov_b32_e32 v67, v66
	v_mov_b32_e32 v68, v66
	v_mov_b32_e32 v69, v66
	v_mov_b32_e32 v70, v66
	v_mov_b32_e32 v71, v66
	v_mov_b32_e32 v72, v66
	v_mov_b32_e32 v73, v66
	v_mov_b32_e32 v74, v66
	v_mov_b32_e32 v75, v66
	v_mov_b32_e32 v76, v66
	v_mov_b32_e32 v77, v66
	v_mov_b32_e32 v78, v66
	v_mov_b32_e32 v79, v66
	v_mov_b32_e32 v80, v66
	v_mov_b32_e32 v81, v66
	v_mov_b32_e32 v82, v66
	v_mov_b32_e32 v83, v66
	v_mov_b32_e32 v84, v66
	v_mov_b32_e32 v85, v66
	v_mov_b32_e32 v86, v66
	v_mov_b32_e32 v87, v66
	v_mov_b32_e32 v88, v66
	v_mov_b32_e32 v89, v66
	v_mov_b32_e32 v90, v66
	v_mov_b32_e32 v91, v66
	v_mov_b32_e32 v92, v66
	v_mov_b32_e32 v93, v66
	v_mov_b32_e32 v94, v66
	v_mov_b32_e32 v95, v66
	v_mov_b32_e32 v96, v66
	v_mov_b32_e32 v97, v66
	v_mov_b32_e32 v98, v66
	v_mov_b32_e32 v99, v66
	v_mov_b32_e32 v100, v66
	v_mov_b32_e32 v101, v66
	v_mov_b32_e32 v102, v66
	v_mov_b32_e32 v103, v66
	v_mov_b32_e32 v104, v66
	v_mov_b32_e32 v105, v66
	v_mov_b32_e32 v106, v66
	v_mov_b32_e32 v107, v66
	v_mov_b32_e32 v108, v66
	v_mov_b32_e32 v109, v66
	v_mov_b32_e32 v110, v66
	v_mov_b32_e32 v111, v66
	v_mov_b32_e32 v112, v66
	v_mov_b32_e32 v113, v66
	v_mov_b32_e32 v114, v66
	v_mov_b32_e32 v115, v66
	v_mov_b32_e32 v116, v66
	v_mov_b32_e32 v117, v66
	v_mov_b32_e32 v118, v66
	v_mov_b32_e32 v119, v66
	v_mov_b32_e32 v120, v66
	v_mov_b32_e32 v121, v66
	v_mov_b32_e32 v122, v66
	v_mov_b32_e32 v123, v66
	v_mov_b32_e32 v124, v66
	v_mov_b32_e32 v125, v66
	v_mov_b32_e32 v126, v66
	v_mov_b32_e32 v127, v66
	v_mov_b32_e32 v128, v66
	v_mov_b32_e32 v129, v66
	v_mov_b32_e32 v62, v66
	v_mov_b32_e32 v63, v66
	v_mov_b32_e32 v64, v66
	v_mov_b32_e32 v65, v66
	v_mov_b32_e32 v58, v66
	v_mov_b32_e32 v59, v66
	v_mov_b32_e32 v60, v66
	v_mov_b32_e32 v61, v66
	v_mov_b32_e32 v54, v66
	v_mov_b32_e32 v55, v66
	v_mov_b32_e32 v56, v66
	v_mov_b32_e32 v57, v66
	v_mov_b32_e32 v50, v66
	v_mov_b32_e32 v51, v66
	v_mov_b32_e32 v52, v66
	v_mov_b32_e32 v53, v66
	v_mov_b32_e32 v46, v66
	v_mov_b32_e32 v47, v66
	v_mov_b32_e32 v48, v66
	v_mov_b32_e32 v49, v66
	v_mov_b32_e32 v42, v66
	v_mov_b32_e32 v43, v66
	v_mov_b32_e32 v44, v66
	v_mov_b32_e32 v45, v66
	v_mov_b32_e32 v38, v66
	v_mov_b32_e32 v39, v66
	v_mov_b32_e32 v40, v66
	v_mov_b32_e32 v41, v66
	v_mov_b32_e32 v34, v66
	v_mov_b32_e32 v35, v66
	v_mov_b32_e32 v36, v66
	v_mov_b32_e32 v37, v66
	v_mov_b32_e32 v30, v66
	v_mov_b32_e32 v31, v66
	v_mov_b32_e32 v32, v66
	v_mov_b32_e32 v33, v66
	v_mov_b32_e32 v26, v66
	v_mov_b32_e32 v27, v66
	v_mov_b32_e32 v28, v66
	v_mov_b32_e32 v29, v66
	v_mov_b32_e32 v22, v66
	v_mov_b32_e32 v23, v66
	v_mov_b32_e32 v24, v66
	v_mov_b32_e32 v25, v66
	v_mov_b32_e32 v18, v66
	v_mov_b32_e32 v19, v66
	v_mov_b32_e32 v20, v66
	v_mov_b32_e32 v21, v66
	v_mov_b32_e32 v14, v66
	v_mov_b32_e32 v15, v66
	v_mov_b32_e32 v16, v66
	v_mov_b32_e32 v17, v66
	v_mov_b32_e32 v10, v66
	v_mov_b32_e32 v11, v66
	v_mov_b32_e32 v12, v66
	v_mov_b32_e32 v13, v66
	v_mov_b32_e32 v6, v66
	v_mov_b32_e32 v7, v66
	v_mov_b32_e32 v8, v66
	v_mov_b32_e32 v9, v66
	v_mov_b32_e32 v2, v66
	v_mov_b32_e32 v3, v66
	v_mov_b32_e32 v4, v66
	v_mov_b32_e32 v5, v66
	v_readfirstlane_b32 s46, v204
	s_nop 3
	s_lshr_b32 s46, s46, 8
	s_cmp_eq_u32 s46, 0
	s_cbranch_scc0 .Lgprio_done
	s_setprio 1
